# NA next-unit warm-up no longer touches the context rows (already L2-resident across units): 3 dummy loads instead of 4 (probe: -2us in NA)
# baseline (speedup 1.0000x reference)
.LBB0_1387:
	s_or_b64 exec, exec, s[4:5]
	v_lshrrev_b32_e32 v14, 2, v2
	v_ashrrev_i32_e32 v17, 8, v2
	v_and_b32_e32 v20, 48, v14
	v_add_u32_e32 v19, s6, v17
	v_sub_u32_e64 v14, v20, 8 clamp
	v_min_u32_e32 v140, 32, v14
	v_lshlrev_b32_e32 v14, 6, v19
	s_and_b32 s36, s34, 30
	v_and_b32_e32 v139, 15, v2
	v_ashrrev_i32_e32 v15, 31, v14
	v_sub_u32_e64 v0, s36, 4 clamp
	v_lshl_add_u64 v[14:15], s[0:1], 0, v[14:15]
	v_or_b32_e32 v20, v20, v139
	v_min_u32_e32 v0, 24, v0
	v_or_b32_e32 v14, v20, v14
	s_lshl_b32 s4, s7, 6
	v_lshlrev_b32_e32 v13, 13, v0
	v_max_i32_e32 v0, 4, v19
	v_lshlrev_b64 v[118:119], 9, v[14:15]
	v_lshlrev_b64 v[14:15], 10, v[14:15]
	v_add_u32_e32 v0, -4, v0
	v_bfe_u32 v98, v2, 4, 2
	v_lshl_add_u64 v[14:15], s[64:65], 0, v[14:15]
	s_lshl_b32 s26, s4, 1
	v_min_u32_e32 v21, 24, v0
	v_lshl_add_u64 v[14:15], v[14:15], 0, s[26:27]
	v_lshlrev_b32_e32 v0, 4, v98
	v_lshl_add_u64 v[14:15], v[14:15], 0, v[0:1]
	v_sub_u32_e64 v14, v20, 8 clamp
	v_lshlrev_b32_e32 v141, 2, v98
	v_min_u32_e32 v14, 48, v14
	v_add_u32_e32 v15, v140, v141
	v_add_u32_e32 v66, 16, v14
	v_sub_u32_e32 v67, v15, v20
	v_cmp_ge_u32_e32 vcc, v15, v14
	v_cmp_lt_u32_e64 s[0:1], v15, v66
	v_med3_i32 v142, v67, -15, 15
	v_or_b32_e32 v67, 1, v15
	s_and_b64 s[4:5], vcc, s[0:1]
	v_cmp_ge_u32_e32 vcc, v67, v14
	v_cmp_lt_u32_e64 s[0:1], v67, v66
	v_sub_u32_e32 v67, v67, v20
	v_med3_i32 v143, v67, -15, 15
	v_or_b32_e32 v67, 2, v15
	s_and_b64 s[6:7], vcc, s[0:1]
	v_cmp_ge_u32_e32 vcc, v67, v14
	v_cmp_lt_u32_e64 s[0:1], v67, v66
	v_sub_u32_e32 v67, v67, v20
	v_med3_i32 v144, v67, -15, 15
	v_or_b32_e32 v67, 3, v15
	s_and_b64 s[8:9], vcc, s[0:1]
	v_cmp_ge_u32_e32 vcc, v67, v14
	v_cmp_lt_u32_e64 s[0:1], v67, v66
	v_sub_u32_e32 v67, v67, v20
	v_med3_i32 v145, v67, -15, 15
	v_add_u32_e32 v67, 16, v15
	s_and_b64 s[10:11], vcc, s[0:1]
	v_cmp_ge_u32_e32 vcc, v67, v14
	v_sub_u32_e32 v67, v67, v20
	v_cmp_lt_u32_e64 s[0:1], v15, v14
	v_med3_i32 v146, v67, -15, 15
	v_add_u32_e32 v67, 17, v15
	s_and_b64 s[12:13], vcc, s[0:1]
	v_cmp_ge_u32_e32 vcc, v67, v14
	v_cmp_lt_u32_e64 s[0:1], v67, v66
	v_sub_u32_e32 v67, v67, v20
	v_med3_i32 v147, v67, -15, 15
	v_add_u32_e32 v67, 18, v15
	s_and_b64 s[14:15], vcc, s[0:1]
	v_cmp_ge_u32_e32 vcc, v67, v14
	v_cmp_lt_u32_e64 s[0:1], v67, v66
	v_add_u32_e32 v15, 19, v15
	s_and_b64 s[16:17], vcc, s[0:1]
	v_cmp_ge_u32_e32 vcc, v15, v14
	v_cmp_lt_u32_e64 s[0:1], v15, v66
	v_or_b32_e32 v120, 0x1d400, v0
	v_sub_u32_e32 v67, v67, v20
	s_and_b64 s[18:19], vcc, s[0:1]
	v_mad_u32_u24 v0, v139, s42, v120
	v_cmp_lt_i32_e32 vcc, v135, v136
	v_med3_i32 v148, v67, -15, 15
	s_waitcnt lgkmcnt(0)
	s_barrier
	s_add_i32 s98, s48, 1
	s_lshl_b32 s98, s98, 3
	s_or_b32 s98, s98, s3
	s_mul_i32 s98, s98, s21
	s_add_i32 s98, s98, s20
	s_min_i32 s98, s98, 0x7ff
	s_bfe_u32 s99, s98, 0x30004
	s_lshl_b32 s99, s99, 7
	s_and_b32 s100, s98, 15
	s_lshl_b32 s100, s100, 1
	s_sub_i32 s100, s100, 4
	s_max_i32 s100, s100, 0
	s_min_i32 s100, s100, 24
	s_lshl_b32 s100, s100, 6
	s_ashr_i32 s101, s98, 7
	s_lshl_b32 s98, s101, 11
	s_add_i32 s100, s100, s98
	s_lshl_b32 s101, s101, 8
	s_add_i32 s101, s101, 0x8000
	v_cmp_gt_u32_e32 vcc, 0x100, v162
	v_mov_b32_e32 v238, 0x4400000
	v_mov_b32_e32 v239, 0x2000000
	s_nop 0
	v_cndmask_b32_e32 v238, v239, v238, vcc
	v_add_u32_e32 v238, s99, v238
	v_and_b32_e32 v236, 0xff, v162
	v_and_b32_e32 v237, 63, v162
	v_add_u32_e32 v240, s101, v236
	v_lshl_add_u32 v240, v240, 10, v238
	v_mov_b32_e32 v241, 0
	v_add_u32_e32 v242, s100, v236
	v_lshl_add_u32 v242, v242, 10, v238
	v_mov_b32_e32 v243, 0
	v_add_u32_e32 v244, 0x40000, v242
	v_mov_b32_e32 v245, 0
	v_add_u32_e32 v237, s100, v237
	v_add_u32_e32 v237, 0x200, v237
	v_lshl_add_u32 v236, v237, 10, v238
	v_mov_b32_e32 v237, 0
	v_lshl_add_u64 v[240:241], s[64:65], 0, v[240:241]
	v_lshl_add_u64 v[242:243], s[64:65], 0, v[242:243]
	v_lshl_add_u64 v[244:245], s[64:65], 0, v[244:245]
	v_lshl_add_u64 v[236:237], s[64:65], 0, v[236:237]
	global_load_dword v216, v[242:243], off
	global_load_dword v217, v[244:245], off
	global_load_dword v218, v[236:237], off
	ds_read_b128 v[66:69], v0
	ds_read_b128 v[70:73], v0 offset:64
	ds_read_b128 v[74:77], v0 offset:2304
	ds_read_b128 v[78:81], v0 offset:2368
	ds_read_b128 v[82:85], v0 offset:4608
	ds_read_b128 v[86:89], v0 offset:4672
	ds_read_b128 v[90:93], v0 offset:6912
	ds_read_b128 v[94:97], v0 offset:6976
	v_cndmask_b32_e32 v0, v134, v135, vcc
	v_cmp_lt_i32_e32 vcc, v137, v136
	v_lshlrev_b32_e32 v150, 2, v0
	v_sub_u32_e32 v153, v21, v7
	v_cndmask_b32_e32 v0, v134, v137, vcc
	v_lshlrev_b32_e32 v151, 2, v0
	v_bfe_u32 v0, v2, 2, 2
	v_or_b32_e32 v0, v141, v0
	v_mul_u32_u24_e32 v152, 0x90, v0
	v_lshlrev_b32_e32 v0, 2, v2
	v_sub_u32_e32 v14, v15, v20
	v_and_b32_e32 v20, 12, v0
	v_lshl_or_b32 v0, v153, 6, v140
	v_add_lshl_u32 v0, v0, v139, 7
	v_add_u32_e32 v154, 0x14400, v0
	v_add_u32_e32 v157, 0x14c00, v0
	v_add_u32_e32 v158, 0x16400, v0
	v_add_u32_e32 v159, 0x16c00, v0
	v_xor_b32_e32 v0, v3, v2
	v_lshlrev_b32_e32 v0, 4, v0
	v_and_b32_e32 v0, 0x70, v0
	v_lshl_or_b32 v0, v3, 7, v0
	v_add_u32_e32 v161, 0x14400, v0
	v_xor_b32_e32 v0, v4, v2
	v_lshlrev_b32_e32 v0, 4, v0
	v_and_b32_e32 v0, 0x70, v0
	v_lshl_or_b32 v0, v4, 7, v0
	v_add_u32_e32 v164, 0x14400, v0
	v_xor_b32_e32 v0, v5, v2
	v_lshlrev_b32_e32 v0, 4, v0
	v_and_b32_e32 v0, 0x70, v0
	v_lshl_or_b32 v0, v5, 7, v0
	v_add_u32_e32 v165, 0x14400, v0
	v_xor_b32_e32 v0, v6, v2
	v_lshlrev_b32_e32 v0, 4, v0
	v_and_b32_e32 v0, 0x70, v0
	v_lshl_or_b32 v0, v6, 7, v0
	v_add_u32_e32 v166, 0x14400, v0
	v_xor_b32_e32 v0, v12, v2
	v_lshlrev_b32_e32 v0, 4, v0
	v_and_b32_e32 v0, 0x70, v0
	v_lshl_or_b32 v0, v12, 7, v0
	v_add_u32_e32 v167, 0x14400, v0
	v_xor_b32_e32 v0, v11, v2
	v_lshlrev_b32_e32 v0, 4, v0
	v_and_b32_e32 v0, 0x70, v0
	v_lshl_or_b32 v0, v11, 7, v0
	v_add_u32_e32 v168, 0x14400, v0
	v_xor_b32_e32 v0, v10, v2
	v_lshlrev_b32_e32 v0, 4, v0
	v_and_b32_e32 v0, 0x70, v0
	v_lshl_or_b32 v0, v10, 7, v0
	v_add_u32_e32 v169, 0x14400, v0
	v_xor_b32_e32 v0, v9, v2
	v_lshlrev_b32_e32 v0, 4, v0
	v_and_b32_e32 v0, 0x70, v0
	v_lshl_or_b32 v0, v9, 7, v0
	v_add_u32_e32 v170, 0x14400, v0
	v_xor_b32_e32 v0, v8, v2
	v_lshlrev_b32_e32 v0, 4, v0
	v_and_b32_e32 v0, 0x70, v0
	v_lshl_or_b32 v0, v8, 7, v0
	v_add_u32_e32 v171, 0x14400, v0
	v_add_u32_e32 v0, s36, v17
	v_max_i32_e32 v0, 4, v0
	v_lshrrev_b32_e32 v16, 4, v2
	v_and_b32_e32 v7, 7, v2
	v_add_u32_e32 v0, -4, v0
	v_med3_i32 v149, v14, -15, 15
	v_bitop3_b32 v14, v16, v7, 3 bitop3:0x6c
	v_bitop3_b32 v7, v98, v7, 4 bitop3:0x36
	v_min_u32_e32 v0, 24, v0
	v_add_lshl_u32 v2, v140, v139, 7
	v_lshlrev_b32_e32 v155, 4, v14
	v_lshlrev_b32_e32 v156, 4, v7
	v_lshl_add_u32 v0, v0, 13, v2
	v_or_b32_e32 v2, v0, v156
	v_or_b32_e32 v0, v0, v155
	v_sub_u32_e32 v173, v2, v13
	v_sub_u32_e32 v174, v0, v13
	v_mov_b32_e32 v2, v1
	v_mov_b32_e32 v3, v1
	v_mov_b32_e32 v4, v1
	v_mov_b32_e32 v5, v1
	v_mov_b32_e32 v6, v1
	v_mov_b32_e32 v7, v1
	v_mov_b32_e32 v8, v1
	v_mov_b32_e32 v9, v1
	v_mov_b32_e32 v10, v1
	v_mov_b32_e32 v11, v1
	v_mov_b32_e32 v12, v1
	v_mov_b32_e32 v13, v1
	v_mov_b32_e32 v14, v1
	v_mov_b32_e32 v15, v1
	v_mov_b32_e32 v0, v1
	v_mov_b64_e32 v[16:17], v[14:15]
	s_mov_b32 s28, 0
	v_sub_u32_e32 v160, v21, v19
	v_or_b32_e32 v172, 64, v140
	v_mov_b32_e32 v98, v1
	v_mov_b32_e32 v99, v1
	v_mov_b32_e32 v100, v1
	v_mov_b32_e32 v101, v1
	v_mov_b32_e32 v175, 0
	s_mov_b32 s49, 0x15600
	v_lshlrev_b32_e32 v176, 1, v20
	s_mov_b32 s50, 0
	v_mov_b64_e32 v[14:15], v[12:13]
	v_mov_b64_e32 v[12:13], v[10:11]
	v_mov_b64_e32 v[10:11], v[8:9]
	v_mov_b64_e32 v[8:9], v[6:7]
	v_mov_b64_e32 v[6:7], v[4:5]
	v_mov_b64_e32 v[4:5], v[2:3]
	v_mov_b64_e32 v[2:3], v[0:1]
	s_branch .LBB0_1389

.LBB0_1391:
	v_xor_b32_e32 v106, 0x80000000, v175
	v_mov_b32_e32 v107, v106
	v_mov_b32_e32 v108, v106
	v_mov_b32_e32 v109, v106
	s_and_b32 s51, s50, 3
	s_cmp_eq_u32 s51, 3
	s_waitcnt vmcnt(4) lgkmcnt(7)
	v_mfma_f32_16x16x32_bf16 v[102:105], v[66:69], v[58:61], v[106:109]
	s_waitcnt vmcnt(3) lgkmcnt(6)
	v_mfma_f32_16x16x32_bf16 v[110:113], v[70:73], v[62:65], v[102:105]
	s_waitcnt lgkmcnt(5)
	v_mfma_f32_16x16x32_bf16 v[102:105], v[74:77], v[58:61], v[106:109]
	s_waitcnt lgkmcnt(4)
	v_mfma_f32_16x16x32_bf16 v[114:117], v[78:81], v[62:65], v[102:105]
	s_waitcnt lgkmcnt(3)
	v_mfma_f32_16x16x32_bf16 v[102:105], v[82:85], v[58:61], v[106:109]
	s_waitcnt lgkmcnt(1)
	v_mfma_f32_16x16x32_bf16 v[106:109], v[90:93], v[58:61], v[106:109]
	v_mfma_f32_16x16x32_bf16 v[102:105], v[86:89], v[62:65], v[102:105]
	s_waitcnt lgkmcnt(0)
	v_mfma_f32_16x16x32_bf16 v[106:109], v[94:97], v[62:65], v[106:109]
	s_cbranch_scc1 .LBB0_1397
	s_cmp_gt_u32 s50, 2
	s_mov_b64 s[0:1], -1
	s_cbranch_scc0 .LBB0_1394
	v_add_u32_e32 v21, s28, v174
	v_add_u32_e32 v70, s28, v173
	v_add_u32_e32 v20, 0x8400, v21
	v_add_u32_e32 v0, 0x8400, v70
	v_add_u32_e32 v19, 0x8c00, v21
	v_add_u32_e32 v66, 0x8c00, v70
	v_add_u32_e32 v67, 0xa400, v21
	v_add_u32_e32 v68, 0xa400, v70
	v_add_u32_e32 v69, 0xac00, v21
	v_add_u32_e32 v21, 0xac00, v70
	s_mov_b64 s[0:1], 0
